# loads hoisted above the barrier that only guards their LDS writes: lora weight rows of a head in the RWKV prep loop, compressed K/V tile in the compressed-attention task, next key block in the cross-a
# baseline (speedup 1.0000x reference)
.LBB0_1770:
	s_nop 0
	v_lshl_add_u64 v[0:1], v[158:159], 0, s[16:17]
	v_add_co_u32_e32 v8, vcc, 0x7000000, v0
	v_lshl_add_u64 v[24:25], v[164:165], 0, s[16:17]
	s_nop 0
	v_addc_co_u32_e32 v9, vcc, 0, v1, vcc
	global_load_dwordx4 v[20:23], v[8:9], off
	global_load_dwordx4 v[60:63], v[8:9], off offset:64
	global_load_dwordx4 v[16:19], v[24:25], off offset:-1088
	global_load_dwordx4 v[56:59], v[24:25], off offset:-1024
	global_load_dwordx4 v[68:71], v[8:9], off offset:1024
	global_load_dwordx4 v[4:7], v[8:9], off offset:1088
	global_load_dwordx4 v[64:67], v[24:25], off offset:-64
	global_load_dwordx4 v[0:3], v[24:25], off
	global_load_dwordx4 v[12:15], v[8:9], off offset:2048
	global_load_dwordx4 v[52:55], v[8:9], off offset:2112
	s_nop 0
	global_load_dwordx4 v[8:11], v[24:25], off offset:960
	global_load_dwordx4 v[48:51], v[24:25], off offset:1024
	v_lshl_add_u64 v[24:25], s[96:97], 0, v[174:175]
	v_add_co_u32_e32 v26, vcc, 0x2900000, v24
	s_nop 1
	v_addc_co_u32_e32 v27, vcc, 0, v25, vcc
	global_load_dwordx4 v[208:211], v[26:27], off
	v_add_co_u32_e32 v24, vcc, 0x2910000, v24
	s_nop 1
	v_addc_co_u32_e32 v25, vcc, 0, v25, vcc
	global_load_dwordx4 v[212:215], v[24:25], off
	v_lshl_add_u64 v[24:25], s[96:97], 0, v[170:171]
	v_lshl_add_u64 v[28:29], s[96:97], 0, v[172:173]
	global_load_dwordx4 v[24:27], v[24:25], off
	s_nop 0
	global_load_dwordx4 v[28:31], v[28:29], off
	s_waitcnt lgkmcnt(0)
	s_barrier
	s_waitcnt vmcnt(2)
	ds_write_b128 v195, v[208:211]
	ds_write_b128 v197, v[212:215] offset:9216
	s_nop 1
	s_branch .Lprep_rest

.LBB0_2007:
	s_ashr_i32 s12, s33, 4
	s_ashr_i32 s13, s12, 31
	s_lshl_b64 s[0:1], s[12:13], 14
	v_lshl_add_u64 v[8:9], v[40:41], 0, s[0:1]
	v_lshl_add_u64 v[10:11], v[42:43], 0, s[0:1]
	v_mov_b32_e32 v53, v37
	v_mov_b32_e32 v55, v37
	v_mov_b32_e32 v57, v37
	v_mov_b32_e32 v59, v37
	s_waitcnt lgkmcnt(0)
	v_lshl_add_u64 v[0:1], v[8:9], 0, v[52:53]
	v_lshl_add_u64 v[4:5], v[10:11], 0, v[54:55]
	v_lshl_add_u64 v[8:9], v[8:9], 0, v[56:57]
	v_lshl_add_u64 v[12:13], v[10:11], 0, v[58:59]
	global_load_dwordx4 v[0:3], v[0:1], off
	s_nop 0
	global_load_dwordx4 v[4:7], v[4:5], off
	s_nop 0
	global_load_dwordx4 v[8:11], v[8:9], off
	s_nop 0
	global_load_dwordx4 v[12:15], v[12:13], off
	s_barrier
	s_lshl_b32 s13, s33, 3
	s_lshr_b32 s1, s95, 3
	s_lshl_b32 s90, s12, 7
	s_and_b32 s12, s13, 0x78
	v_readlane_b32 s18, v251, 7
	s_lshl_b32 s1, s1, 7
	s_add_i32 s12, s12, s18
	s_add_i32 s1, s7, s1
	s_add_i32 s14, s12, s90
	s_and_b32 s1, s1, 0x7f0
	s_lshl_b32 s13, s12, 4
	s_ashr_i32 s12, s14, 8
	v_or_b32_e32 v17, s1, v99
	s_and_b32 s1, s13, 0x7f0
	s_ashr_i32 s13, s12, 31
	s_and_b32 s15, s95, 0x78
	s_lshl_b64 s[24:25], s[12:13], 17
	v_add_u32_e32 v16, v140, v196
	v_or_b32_e32 v53, s1, v99
	s_add_u32 s16, s24, 0x13000000
	v_subrev_u32_e32 v18, 31, v53
	s_addc_u32 s17, s25, 0
	v_lshrrev_b32_e32 v18, 4, v18
	v_add_u32_e32 v18, 1, v18
	v_cmp_lt_u32_e32 vcc, 30, v53
	v_lshlrev_b32_e32 v36, 10, v17
	v_mov_b32_e32 v86, 0
	v_cndmask_b32_e32 v18, 0, v18, vcc
	s_lshl_b64 vcc, s[12:13], 21
	s_mov_b32 s0, 4
	v_cmp_lt_u32_e64 s[24:25], v194, v18
	v_cmp_lt_u32_e64 s[26:27], v101, v18
	v_cmp_lt_u32_e64 s[28:29], v102, v18
	v_cmp_lt_u32_e64 s[30:31], v103, v18
	v_cmp_lt_u32_e64 s[34:35], v104, v18
	v_cmp_lt_u32_e64 s[36:37], v105, v18
	v_cmp_lt_u32_e64 s[38:39], v106, v18
	v_cmp_lt_u32_e64 s[40:41], v107, v18
	v_cmp_lt_u32_e64 s[42:43], v108, v18
	v_cmp_lt_u32_e64 s[44:45], v109, v18
	v_cmp_lt_u32_e64 s[46:47], v110, v18
	v_cmp_lt_u32_e64 s[48:49], v111, v18
	v_cmp_lt_u32_e64 s[50:51], v112, v18
	v_cmp_lt_u32_e64 s[52:53], v113, v18
	v_cmp_lt_u32_e64 s[54:55], v114, v18
	v_cmp_lt_u32_e64 s[56:57], v115, v18
	v_cmp_lt_u32_e64 s[58:59], v116, v18
	v_cmp_lt_u32_e64 s[60:61], v117, v18
	v_cmp_lt_u32_e64 s[62:63], v118, v18
	v_cmp_lt_u32_e64 s[64:65], v119, v18
	v_cmp_lt_u32_e64 s[66:67], v120, v18
	v_cmp_lt_u32_e64 s[68:69], v121, v18
	v_cmp_lt_u32_e64 s[70:71], v122, v18
	v_cmp_lt_u32_e64 s[72:73], v123, v18
	v_cmp_lt_u32_e64 s[74:75], v124, v18
	v_cmp_lt_u32_e64 s[76:77], v125, v18
	v_cmp_lt_u32_e64 s[78:79], v126, v18
	v_cmp_lt_u32_e64 s[80:81], v127, v18
	v_cmp_lt_u32_e64 s[82:83], v128, v18
	v_cmp_lt_u32_e64 s[84:85], v129, v18
	v_cmp_lt_u32_e64 s[86:87], v130, v18
	v_cmp_lt_u32_e64 s[88:89], v131, v18
	v_mov_b32_e32 v93, s17
	v_mov_b32_e32 v95, vcc_hi
	v_mov_b32_e32 v87, v86
	v_mov_b32_e32 v84, v86
	v_mov_b32_e32 v85, v86
	s_waitcnt vmcnt(3)
	ds_write_b128 v16, v[0:3]
	s_waitcnt vmcnt(2)
	ds_write_b128 v148, v[4:7] offset:18432
	s_waitcnt vmcnt(1)
	ds_write_b128 v149, v[8:11]
	s_waitcnt vmcnt(0)
	ds_write_b128 v150, v[12:15] offset:18432
	v_lshl_or_b32 v0, v17, 6, s16
	s_add_i32 s16, s18, s90
	s_add_i32 s16, s16, s15
	s_bfe_u32 s15, s16, 0x10007
	s_mul_i32 s15, s15, 24
	s_lshl_b32 s13, s16, 2
	v_or_b32_e32 v92, s15, v0
	v_or_b32_e32 v0, vcc_lo, v154
	s_and_b32 s90, s13, 0x200
	v_or3_b32 v94, v0, v36, s90
	v_lshl_add_u64 v[0:1], v[50:51], 0, vcc
	v_lshl_add_u64 v[0:1], v[0:1], 0, v[36:37]
	v_lshl_add_u64 v[96:97], v[0:1], 0, s[90:91]
	v_mov_b32_e32 v90, v86
	v_mov_b32_e32 v91, v86
	v_mov_b32_e32 v88, v86
	v_mov_b32_e32 v89, v86
	v_mov_b32_e32 v80, v86
	v_mov_b32_e32 v81, v86
	v_mov_b32_e32 v76, v86
	v_mov_b32_e32 v77, v86
	v_mov_b32_e32 v82, v86
	v_mov_b32_e32 v83, v86
	v_mov_b32_e32 v78, v86
	v_mov_b32_e32 v79, v86
	v_mov_b32_e32 v72, v86
	v_mov_b32_e32 v73, v86
	v_mov_b32_e32 v68, v86
	v_mov_b32_e32 v69, v86
	v_mov_b32_e32 v74, v86
	v_mov_b32_e32 v75, v86
	v_mov_b32_e32 v70, v86
	v_mov_b32_e32 v71, v86
	v_mov_b32_e32 v64, v86
	v_mov_b32_e32 v65, v86
	v_mov_b32_e32 v60, v86
	v_mov_b32_e32 v61, v86
	v_mov_b32_e32 v66, v86
	v_mov_b32_e32 v67, v86
	v_mov_b32_e32 v62, v86
	v_mov_b32_e32 v63, v86
	v_lshl_add_u64 v[214:215], s[96:97], 0, v[94:95]
	s_mov_b32 s13, 0xe000000
	v_add_co_u32_e32 v214, vcc, s13, v214
	s_nop 1
	v_addc_co_u32_e32 v215, vcc, 0, v215, vcc
	global_load_dwordx4 v[204:207], v[214:215], off
	global_load_dwordx4 v[208:211], v[214:215], off offset:64
	v_lshl_add_u64 v[214:215], s[96:97], 0, v[92:93]
	global_load_ushort v212, v[214:215], off
	s_waitcnt lgkmcnt(0)
	s_barrier
	s_waitcnt vmcnt(0)

.LBB0_2492:
	s_and_b64 s[20:21], s[14:15], exec
	s_cselect_b32 s20, 0x11400, 0
	s_add_i32 s20, s20, 0
	v_add_u32_e32 v129, s20, v141
	v_add_u32_e32 v130, s20, v140
	v_add_u32_e32 v131, v129, v205
	s_waitcnt vmcnt(7)
	ds_write_b128 v131, v[60:63]
	v_add_u32_e32 v131, v130, v206
	s_waitcnt vmcnt(6)
	ds_write_b128 v131, v[64:67] offset:33792
	v_add_u32_e32 v131, v129, v207
	s_waitcnt vmcnt(5)
	ds_write_b128 v131, v[72:75]
	v_add_u32_e32 v131, v130, v208
	s_waitcnt vmcnt(4)
	ds_write_b128 v131, v[80:83] offset:33792
	v_add_u32_e32 v131, v129, v209
	s_waitcnt vmcnt(3)
	ds_write_b128 v131, v[84:87]
	v_add_u32_e32 v131, v130, v210
	v_add_u32_e32 v129, v129, v211
	s_waitcnt vmcnt(2)
	ds_write_b128 v131, v[88:91] offset:33792
	s_waitcnt vmcnt(1)
	ds_write_b128 v129, v[100:103]
	v_add_u32_e32 v129, v130, v212
	s_cmp_eq_u32 s6, 1
	s_waitcnt vmcnt(0)
	ds_write_b128 v129, v[104:107] offset:33792
	s_cbranch_scc1 .Lxa_noload
	v_lshl_add_u64 v[60:61], s[96:97], 0, v[198:199]
	v_lshl_add_u64 v[64:65], s[96:97], 0, v[192:193]
	v_lshl_add_u64 v[72:73], s[96:97], 0, v[196:197]
	v_lshl_add_u64 v[80:81], s[96:97], 0, v[190:191]
	v_lshl_add_u64 v[84:85], s[96:97], 0, v[194:195]
	v_lshl_add_u64 v[88:89], s[96:97], 0, v[188:189]
	v_lshl_add_u64 v[100:101], s[96:97], 0, v[200:201]
	v_lshl_add_u64 v[104:105], s[96:97], 0, v[186:187]
	global_load_dwordx4 v[60:63], v[60:61], off
	s_nop 0
	global_load_dwordx4 v[64:67], v[64:65], off
	s_nop 0
	global_load_dwordx4 v[72:75], v[72:73], off
	s_nop 0
	global_load_dwordx4 v[80:83], v[80:81], off
	s_nop 0
	global_load_dwordx4 v[84:87], v[84:85], off
	s_nop 0
	global_load_dwordx4 v[88:91], v[88:89], off
	s_nop 0
	global_load_dwordx4 v[100:103], v[100:101], off
	s_nop 0
	global_load_dwordx4 v[104:107], v[104:105], off
.Lxa_noload:
	s_waitcnt lgkmcnt(0)
	s_barrier
.LBB0_2494:
	v_add3_u32 v244, s20, v203, v213
	v_add3_u32 v245, s20, v203, v214
	v_add3_u32 v219, s20, v136, v204
	v_mov_b32_e32 v175, v128
	s_xor_b64 s[14:15], s[14:15], -1
	s_add_i32 s6, s6, -1
	ds_read_b128 v[220:223], v244 offset:0
	ds_read_b128 v[224:227], v244 offset:64
	ds_read_b128 v[228:231], v244 offset:128
	ds_read_b128 v[232:235], v244 offset:192
	v_add_u32_e32 v219, 0x8400, v219
	s_waitcnt lgkmcnt(3)
	v_mfma_f32_16x16x32_bf16 v[236:239], v[220:223], v[20:23], 0
	ds_read_b128 v[220:223], v244 offset:256
	s_waitcnt lgkmcnt(3)
	v_mfma_f32_16x16x32_bf16 v[236:239], v[224:227], v[24:27], v[236:239]
	ds_read_b128 v[224:227], v244 offset:320
	v_lshl_add_u64 v[186:187], v[186:187], 0, s[10:11]
	s_waitcnt lgkmcnt(3)
	v_mfma_f32_16x16x32_bf16 v[236:239], v[228:231], v[28:31], v[236:239]
	ds_read_b128 v[228:231], v244 offset:384
	s_waitcnt lgkmcnt(3)
	v_mfma_f32_16x16x32_bf16 v[236:239], v[232:235], v[32:35], v[236:239]
	ds_read_b128 v[232:235], v244 offset:448
	v_lshl_add_u64 v[188:189], v[188:189], 0, s[10:11]
	s_waitcnt lgkmcnt(3)
	v_mfma_f32_16x16x32_bf16 v[236:239], v[220:223], v[36:39], v[236:239]
	ds_read_b128 v[220:223], v244 offset:8448
	s_waitcnt lgkmcnt(3)
	v_mfma_f32_16x16x32_bf16 v[236:239], v[224:227], v[44:47], v[236:239]
	ds_read_b128 v[224:227], v244 offset:8512
	v_lshl_add_u64 v[190:191], v[190:191], 0, s[10:11]
	s_waitcnt lgkmcnt(3)
	v_mfma_f32_16x16x32_bf16 v[236:239], v[228:231], v[48:51], v[236:239]
	ds_read_b128 v[228:231], v244 offset:8576
	s_waitcnt lgkmcnt(3)
	v_mfma_f32_16x16x32_bf16 v[236:239], v[232:235], v[52:55], v[236:239]
	ds_read_b128 v[232:235], v244 offset:8640
	v_lshl_add_u64 v[192:193], v[192:193], 0, s[10:11]
	s_waitcnt lgkmcnt(3)
	v_mfma_f32_16x16x32_bf16 v[240:243], v[220:223], v[20:23], 0
	ds_read_b128 v[220:223], v244 offset:8704
	s_waitcnt lgkmcnt(3)
	v_mfma_f32_16x16x32_bf16 v[240:243], v[224:227], v[24:27], v[240:243]
	ds_read_b128 v[224:227], v244 offset:8768
	v_lshl_add_u64 v[194:195], v[194:195], 0, s[12:13]
	s_waitcnt lgkmcnt(3)
	v_mfma_f32_16x16x32_bf16 v[240:243], v[228:231], v[28:31], v[240:243]
	ds_read_b128 v[228:231], v244 offset:8832
	s_waitcnt lgkmcnt(3)
	v_mfma_f32_16x16x32_bf16 v[240:243], v[232:235], v[32:35], v[240:243]
	ds_read_b128 v[232:235], v244 offset:8896
	v_lshl_add_u64 v[196:197], v[196:197], 0, s[12:13]
	s_waitcnt lgkmcnt(3)
	v_mfma_f32_16x16x32_bf16 v[240:243], v[220:223], v[36:39], v[240:243]
	ds_read_b128 v[220:223], v244 offset:16896
	v_pk_mul_f32 v[236:237], v[236:237], s[8:9] op_sel_hi:[1,0]
	v_pk_mul_f32 v[238:239], v[238:239], s[8:9] op_sel_hi:[1,0]
	s_waitcnt lgkmcnt(3)
	v_mfma_f32_16x16x32_bf16 v[240:243], v[224:227], v[44:47], v[240:243]
	ds_read_b128 v[224:227], v244 offset:16960
	v_lshl_add_u64 v[198:199], v[198:199], 0, s[12:13]
	s_waitcnt lgkmcnt(3)
	v_mfma_f32_16x16x32_bf16 v[240:243], v[228:231], v[48:51], v[240:243]
	ds_read_b128 v[228:231], v244 offset:17024
	s_waitcnt lgkmcnt(3)
	v_mfma_f32_16x16x32_bf16 v[240:243], v[232:235], v[52:55], v[240:243]
	ds_read_b128 v[232:235], v244 offset:17088
	v_lshl_add_u64 v[200:201], v[200:201], 0, s[12:13]
	s_waitcnt lgkmcnt(3)
	v_mfma_f32_16x16x32_bf16 v[128:131], v[220:223], v[20:23], 0
	ds_read_b128 v[220:223], v244 offset:17152
	s_waitcnt lgkmcnt(3)
	v_mfma_f32_16x16x32_bf16 v[128:131], v[224:227], v[24:27], v[128:131]
	ds_read_b128 v[224:227], v244 offset:17216
	s_waitcnt lgkmcnt(3)
	v_mfma_f32_16x16x32_bf16 v[128:131], v[228:231], v[28:31], v[128:131]
	ds_read_b128 v[228:231], v244 offset:17280
	s_waitcnt lgkmcnt(3)
	v_mfma_f32_16x16x32_bf16 v[128:131], v[232:235], v[32:35], v[128:131]
	ds_read_b128 v[232:235], v244 offset:17344
	s_waitcnt lgkmcnt(3)
	v_mfma_f32_16x16x32_bf16 v[128:131], v[220:223], v[36:39], v[128:131]
	ds_read_b128 v[220:223], v245 offset:0
	v_pk_mul_f32 v[240:241], v[240:241], s[8:9] op_sel_hi:[1,0]
	v_pk_mul_f32 v[242:243], v[242:243], s[8:9] op_sel_hi:[1,0]
	s_waitcnt lgkmcnt(3)
	v_mfma_f32_16x16x32_bf16 v[128:131], v[224:227], v[44:47], v[128:131]
	ds_read_b128 v[224:227], v245 offset:64
	s_waitcnt lgkmcnt(3)
	v_mfma_f32_16x16x32_bf16 v[128:131], v[228:231], v[48:51], v[128:131]
	ds_read_b128 v[228:231], v245 offset:128
	s_waitcnt lgkmcnt(3)
	v_mfma_f32_16x16x32_bf16 v[128:131], v[232:235], v[52:55], v[128:131]
	ds_read_b128 v[232:235], v245 offset:192
	s_waitcnt lgkmcnt(3)
	v_mfma_f32_16x16x32_bf16 v[132:135], v[220:223], v[20:23], 0
	ds_read_b128 v[220:223], v245 offset:256
	s_waitcnt lgkmcnt(3)
	v_mfma_f32_16x16x32_bf16 v[132:135], v[224:227], v[24:27], v[132:135]
	ds_read_b128 v[224:227], v245 offset:320
	s_waitcnt lgkmcnt(3)
	v_mfma_f32_16x16x32_bf16 v[132:135], v[228:231], v[28:31], v[132:135]
	ds_read_b128 v[228:231], v245 offset:384
	s_waitcnt lgkmcnt(3)
	v_mfma_f32_16x16x32_bf16 v[132:135], v[232:235], v[32:35], v[132:135]
	ds_read_b128 v[232:235], v245 offset:448
	s_waitcnt lgkmcnt(3)
	v_mfma_f32_16x16x32_bf16 v[132:135], v[220:223], v[36:39], v[132:135]
	v_pk_mul_f32 v[128:129], v[128:129], s[8:9] op_sel_hi:[1,0]
	v_pk_mul_f32 v[130:131], v[130:131], s[8:9] op_sel_hi:[1,0]
	s_waitcnt lgkmcnt(2)
	v_mfma_f32_16x16x32_bf16 v[132:135], v[224:227], v[44:47], v[132:135]
	s_waitcnt lgkmcnt(1)
	v_mfma_f32_16x16x32_bf16 v[132:135], v[228:231], v[48:51], v[132:135]
	s_waitcnt lgkmcnt(0)
	v_mfma_f32_16x16x32_bf16 v[132:135], v[232:235], v[52:55], v[132:135]
	ds_read_b64 v[228:229], v219 offset:0
	ds_read_b64 v[230:231], v219 offset:32
	ds_read_b64 v[232:233], v219 offset:64
	ds_read_b64 v[234:235], v219 offset:96
	s_nop 3
	v_pk_mul_f32 v[132:133], v[132:133], s[8:9] op_sel_hi:[1,0]
	v_pk_mul_f32 v[134:135], v[134:135], s[8:9] op_sel_hi:[1,0]
	v_max3_f32 v167, v236, v237, v238
	v_max3_f32 v167, v167, v239, v240
	v_max3_f32 v167, v167, v241, v242
	v_max3_f32 v167, v167, v243, v128
	v_max3_f32 v167, v167, v129, v130
	v_max3_f32 v167, v167, v131, v132
	v_max3_f32 v167, v167, v133, v134
	v_max3_f32 v167, v167, s17, v135
	v_mov_b32_e32 v169, v167
	s_nop 1
	v_permlane16_swap_b32_e32 v167, v169
	v_max_f32_e32 v169, v169, v169
	v_max_f32_e32 v167, v167, v167
	v_max_f32_e32 v167, v167, v169
	v_mov_b32_e32 v169, v167
	s_nop 1
	v_permlane32_swap_b32_e32 v167, v169
	v_max3_f32 v165, v175, v167, v169
	v_sub_f32_e32 v173, v175, v165
	v_mul_f32_e32 v173, 0x3fb8aa3b, v173
	v_exp_f32_e32 v138, v173
	v_sub_f32_e32 v236, v236, v165
	v_sub_f32_e32 v237, v237, v165
	v_sub_f32_e32 v238, v238, v165
	v_sub_f32_e32 v239, v239, v165
	v_sub_f32_e32 v240, v240, v165
	v_sub_f32_e32 v241, v241, v165
	v_sub_f32_e32 v242, v242, v165
	v_sub_f32_e32 v243, v243, v165
	v_sub_f32_e32 v128, v128, v165
	v_sub_f32_e32 v129, v129, v165
	v_sub_f32_e32 v130, v130, v165
	v_sub_f32_e32 v131, v131, v165
	v_sub_f32_e32 v132, v132, v165
	v_sub_f32_e32 v133, v133, v165
	v_sub_f32_e32 v134, v134, v165
	v_sub_f32_e32 v135, v135, v165
	v_mul_f32_e32 v236, 0x3fb8aa3b, v236
	v_mul_f32_e32 v237, 0x3fb8aa3b, v237
	v_mul_f32_e32 v238, 0x3fb8aa3b, v238
	v_mul_f32_e32 v239, 0x3fb8aa3b, v239
	v_mul_f32_e32 v240, 0x3fb8aa3b, v240
	v_mul_f32_e32 v241, 0x3fb8aa3b, v241
	v_mul_f32_e32 v242, 0x3fb8aa3b, v242
	v_mul_f32_e32 v243, 0x3fb8aa3b, v243
	v_mul_f32_e32 v128, 0x3fb8aa3b, v128
	v_mul_f32_e32 v129, 0x3fb8aa3b, v129
	v_mul_f32_e32 v130, 0x3fb8aa3b, v130
	v_mul_f32_e32 v131, 0x3fb8aa3b, v131
	v_mul_f32_e32 v132, 0x3fb8aa3b, v132
	v_mul_f32_e32 v133, 0x3fb8aa3b, v133
	v_mul_f32_e32 v134, 0x3fb8aa3b, v134
	v_mul_f32_e32 v135, 0x3fb8aa3b, v135
	v_exp_f32_e32 v236, v236
	v_exp_f32_e32 v237, v237
	v_exp_f32_e32 v238, v238
	v_exp_f32_e32 v239, v239
	v_exp_f32_e32 v240, v240
	v_exp_f32_e32 v241, v241
	v_exp_f32_e32 v242, v242
	v_exp_f32_e32 v243, v243
	v_exp_f32_e32 v128, v128
	v_exp_f32_e32 v129, v129
	v_exp_f32_e32 v130, v130
	v_exp_f32_e32 v131, v131
	v_exp_f32_e32 v132, v132
	v_exp_f32_e32 v133, v133
	v_exp_f32_e32 v134, v134
	v_exp_f32_e32 v135, v135
	v_pk_mul_f32 v[124:125], v[124:125], v[138:139] op_sel_hi:[1,0]
	v_pk_mul_f32 v[126:127], v[126:127], v[138:139] op_sel_hi:[1,0]
	v_pk_mul_f32 v[120:121], v[120:121], v[138:139] op_sel_hi:[1,0]
	v_pk_mul_f32 v[122:123], v[122:123], v[138:139] op_sel_hi:[1,0]
	v_pk_mul_f32 v[116:117], v[116:117], v[138:139] op_sel_hi:[1,0]
	v_pk_mul_f32 v[118:119], v[118:119], v[138:139] op_sel_hi:[1,0]
	v_pk_mul_f32 v[112:113], v[112:113], v[138:139] op_sel_hi:[1,0]
	v_pk_mul_f32 v[114:115], v[114:115], v[138:139] op_sel_hi:[1,0]
	v_pk_mul_f32 v[108:109], v[108:109], v[138:139] op_sel_hi:[1,0]
	v_pk_mul_f32 v[110:111], v[110:111], v[138:139] op_sel_hi:[1,0]
	v_pk_mul_f32 v[96:97], v[96:97], v[138:139] op_sel_hi:[1,0]
	v_pk_mul_f32 v[98:99], v[98:99], v[138:139] op_sel_hi:[1,0]
	v_pk_mul_f32 v[92:93], v[92:93], v[138:139] op_sel_hi:[1,0]
	v_pk_mul_f32 v[94:95], v[94:95], v[138:139] op_sel_hi:[1,0]
	v_pk_mul_f32 v[76:77], v[76:77], v[138:139] op_sel_hi:[1,0]
	v_pk_mul_f32 v[78:79], v[78:79], v[138:139] op_sel_hi:[1,0]
	v_pk_mul_f32 v[68:69], v[68:69], v[138:139] op_sel_hi:[1,0]
	v_pk_mul_f32 v[70:71], v[70:71], v[138:139] op_sel_hi:[1,0]
	v_pk_mul_f32 v[56:57], v[56:57], v[138:139] op_sel_hi:[1,0]
	v_pk_mul_f32 v[58:59], v[58:59], v[138:139] op_sel_hi:[1,0]
	v_pk_mul_f32 v[40:41], v[40:41], v[138:139] op_sel_hi:[1,0]
	v_pk_mul_f32 v[42:43], v[42:43], v[138:139] op_sel_hi:[1,0]
	v_pk_mul_f32 v[16:17], v[16:17], v[138:139] op_sel_hi:[1,0]
	v_pk_mul_f32 v[18:19], v[18:19], v[138:139] op_sel_hi:[1,0]
	v_pk_mul_f32 v[12:13], v[12:13], v[138:139] op_sel_hi:[1,0]
	v_pk_mul_f32 v[14:15], v[14:15], v[138:139] op_sel_hi:[1,0]
	v_pk_mul_f32 v[8:9], v[8:9], v[138:139] op_sel_hi:[1,0]
	v_pk_mul_f32 v[10:11], v[10:11], v[138:139] op_sel_hi:[1,0]
	v_pk_mul_f32 v[4:5], v[4:5], v[138:139] op_sel_hi:[1,0]
	v_pk_mul_f32 v[6:7], v[6:7], v[138:139] op_sel_hi:[1,0]
	v_pk_mul_f32 v[0:1], v[0:1], v[138:139] op_sel_hi:[1,0]
	v_pk_mul_f32 v[2:3], v[2:3], v[138:139] op_sel_hi:[1,0]
	v_add_f32_e32 v171, 0, v236
	v_add_f32_e32 v171, v237, v171
	v_add_f32_e32 v171, v238, v171
	v_add_f32_e32 v171, v239, v171
	v_add_f32_e32 v171, v240, v171
	v_add_f32_e32 v171, v241, v171
	v_add_f32_e32 v171, v242, v171
	v_add_f32_e32 v171, v243, v171
	v_add_f32_e32 v171, v128, v171
	v_add_f32_e32 v171, v129, v171
	v_add_f32_e32 v171, v130, v171
	v_add_f32_e32 v171, v131, v171
	v_add_f32_e32 v171, v132, v171
	v_add_f32_e32 v171, v133, v171
	v_add_f32_e32 v171, v134, v171
	v_add_f32_e32 v171, v135, v171
	v_cvt_pk_bf16_f32 v220, v236, v237
	v_cvt_pk_bf16_f32 v221, v238, v239
	v_cvt_pk_bf16_f32 v222, v240, v241
	v_cvt_pk_bf16_f32 v223, v242, v243
	v_cvt_pk_bf16_f32 v224, v128, v129
	v_cvt_pk_bf16_f32 v225, v130, v131
	v_cvt_pk_bf16_f32 v226, v132, v133
	v_cvt_pk_bf16_f32 v227, v134, v135
	v_fmac_f32_e32 v171, v163, v138
	ds_read_b64 v[236:237], v219 offset:2304
	ds_read_b64 v[238:239], v219 offset:2336
	ds_read_b64 v[240:241], v219 offset:2368
	ds_read_b64 v[242:243], v219 offset:2400
	ds_read_b64 v[128:129], v219 offset:4608
	ds_read_b64 v[130:131], v219 offset:4640
	ds_read_b64 v[132:133], v219 offset:4672
	ds_read_b64 v[134:135], v219 offset:4704
	s_waitcnt lgkmcnt(10)
	s_nop 0
	v_mfma_f32_16x16x32_bf16 v[124:127], v[228:231], v[220:223], v[124:127]
	ds_read_b64 v[228:229], v219 offset:6912
	ds_read_b64 v[230:231], v219 offset:6944
	s_waitcnt lgkmcnt(10)
	v_mfma_f32_16x16x32_bf16 v[124:127], v[232:235], v[224:227], v[124:127]
	ds_read_b64 v[232:233], v219 offset:6976
	ds_read_b64 v[234:235], v219 offset:7008
	s_waitcnt lgkmcnt(10)
	v_mfma_f32_16x16x32_bf16 v[120:123], v[236:239], v[220:223], v[120:123]
	ds_read_b64 v[236:237], v219 offset:9216
	ds_read_b64 v[238:239], v219 offset:9248
	s_waitcnt lgkmcnt(10)
	v_mfma_f32_16x16x32_bf16 v[120:123], v[240:243], v[224:227], v[120:123]
	ds_read_b64 v[240:241], v219 offset:9280
	ds_read_b64 v[242:243], v219 offset:9312
	s_waitcnt lgkmcnt(10)
	v_mfma_f32_16x16x32_bf16 v[116:119], v[128:131], v[220:223], v[116:119]
	ds_read_b64 v[128:129], v219 offset:11520
	ds_read_b64 v[130:131], v219 offset:11552
	s_waitcnt lgkmcnt(10)
	v_mfma_f32_16x16x32_bf16 v[116:119], v[132:135], v[224:227], v[116:119]
	ds_read_b64 v[132:133], v219 offset:11584
	ds_read_b64 v[134:135], v219 offset:11616
	s_waitcnt lgkmcnt(10)
	v_mfma_f32_16x16x32_bf16 v[112:115], v[228:231], v[220:223], v[112:115]
	ds_read_b64 v[228:229], v219 offset:13824
	ds_read_b64 v[230:231], v219 offset:13856
	s_waitcnt lgkmcnt(10)
	v_mfma_f32_16x16x32_bf16 v[112:115], v[232:235], v[224:227], v[112:115]
	ds_read_b64 v[232:233], v219 offset:13888
	ds_read_b64 v[234:235], v219 offset:13920
	s_waitcnt lgkmcnt(10)
	v_mfma_f32_16x16x32_bf16 v[108:111], v[236:239], v[220:223], v[108:111]
	ds_read_b64 v[236:237], v219 offset:16128
	ds_read_b64 v[238:239], v219 offset:16160
	s_waitcnt lgkmcnt(10)
	v_mfma_f32_16x16x32_bf16 v[108:111], v[240:243], v[224:227], v[108:111]
	ds_read_b64 v[240:241], v219 offset:16192
	ds_read_b64 v[242:243], v219 offset:16224
	s_waitcnt lgkmcnt(10)
	v_mfma_f32_16x16x32_bf16 v[96:99], v[128:131], v[220:223], v[96:99]
	ds_read_b64 v[128:129], v219 offset:18432
	ds_read_b64 v[130:131], v219 offset:18464
	s_waitcnt lgkmcnt(10)
	v_mfma_f32_16x16x32_bf16 v[96:99], v[132:135], v[224:227], v[96:99]
	ds_read_b64 v[132:133], v219 offset:18496
	ds_read_b64 v[134:135], v219 offset:18528
	s_waitcnt lgkmcnt(10)
	v_mfma_f32_16x16x32_bf16 v[92:95], v[228:231], v[220:223], v[92:95]
	ds_read_b64 v[228:229], v219 offset:20736
	ds_read_b64 v[230:231], v219 offset:20768
	s_waitcnt lgkmcnt(10)
	v_mfma_f32_16x16x32_bf16 v[92:95], v[232:235], v[224:227], v[92:95]
	ds_read_b64 v[232:233], v219 offset:20800
	ds_read_b64 v[234:235], v219 offset:20832
	s_waitcnt lgkmcnt(10)
	v_mfma_f32_16x16x32_bf16 v[76:79], v[236:239], v[220:223], v[76:79]
	ds_read_b64 v[236:237], v219 offset:23040
	ds_read_b64 v[238:239], v219 offset:23072
	s_waitcnt lgkmcnt(10)
	v_mfma_f32_16x16x32_bf16 v[76:79], v[240:243], v[224:227], v[76:79]
	ds_read_b64 v[240:241], v219 offset:23104
	ds_read_b64 v[242:243], v219 offset:23136
	s_waitcnt lgkmcnt(10)
	v_mfma_f32_16x16x32_bf16 v[68:71], v[128:131], v[220:223], v[68:71]
	ds_read_b64 v[128:129], v219 offset:25344
	ds_read_b64 v[130:131], v219 offset:25376
	s_waitcnt lgkmcnt(10)
	v_mfma_f32_16x16x32_bf16 v[68:71], v[132:135], v[224:227], v[68:71]
	ds_read_b64 v[132:133], v219 offset:25408
	ds_read_b64 v[134:135], v219 offset:25440
	s_waitcnt lgkmcnt(10)
	v_mfma_f32_16x16x32_bf16 v[56:59], v[228:231], v[220:223], v[56:59]
	ds_read_b64 v[228:229], v219 offset:27648
	ds_read_b64 v[230:231], v219 offset:27680
	s_waitcnt lgkmcnt(10)
	v_mfma_f32_16x16x32_bf16 v[56:59], v[232:235], v[224:227], v[56:59]
	ds_read_b64 v[232:233], v219 offset:27712
	ds_read_b64 v[234:235], v219 offset:27744
	s_waitcnt lgkmcnt(10)
	v_mfma_f32_16x16x32_bf16 v[40:43], v[236:239], v[220:223], v[40:43]
	ds_read_b64 v[236:237], v219 offset:29952
	ds_read_b64 v[238:239], v219 offset:29984
	s_waitcnt lgkmcnt(10)
	v_mfma_f32_16x16x32_bf16 v[40:43], v[240:243], v[224:227], v[40:43]
	ds_read_b64 v[240:241], v219 offset:30016
	ds_read_b64 v[242:243], v219 offset:30048
	s_waitcnt lgkmcnt(10)
	v_mfma_f32_16x16x32_bf16 v[16:19], v[128:131], v[220:223], v[16:19]
	ds_read_b64 v[128:129], v219 offset:32256
	ds_read_b64 v[130:131], v219 offset:32288
	s_waitcnt lgkmcnt(10)
	v_mfma_f32_16x16x32_bf16 v[16:19], v[132:135], v[224:227], v[16:19]
	ds_read_b64 v[132:133], v219 offset:32320
	ds_read_b64 v[134:135], v219 offset:32352
	s_waitcnt lgkmcnt(10)
	v_mfma_f32_16x16x32_bf16 v[12:15], v[228:231], v[220:223], v[12:15]
	ds_read_b64 v[228:229], v219 offset:34560
	ds_read_b64 v[230:231], v219 offset:34592
	s_waitcnt lgkmcnt(10)
	v_mfma_f32_16x16x32_bf16 v[12:15], v[232:235], v[224:227], v[12:15]
	ds_read_b64 v[232:233], v219 offset:34624
	ds_read_b64 v[234:235], v219 offset:34656
	s_waitcnt lgkmcnt(10)
	v_mfma_f32_16x16x32_bf16 v[8:11], v[236:239], v[220:223], v[8:11]
	s_waitcnt lgkmcnt(8)
	v_mfma_f32_16x16x32_bf16 v[8:11], v[240:243], v[224:227], v[8:11]
	s_waitcnt lgkmcnt(6)
	v_mfma_f32_16x16x32_bf16 v[4:7], v[128:131], v[220:223], v[4:7]
	s_waitcnt lgkmcnt(4)
	v_mfma_f32_16x16x32_bf16 v[4:7], v[132:135], v[224:227], v[4:7]
	s_waitcnt lgkmcnt(2)
	v_mfma_f32_16x16x32_bf16 v[0:3], v[228:231], v[220:223], v[0:3]
	s_waitcnt lgkmcnt(0)
	v_mfma_f32_16x16x32_bf16 v[0:3], v[232:235], v[224:227], v[0:3]
	v_mov_b32_e32 v129, v171
	s_cmp_lg_u32 s6, 0
	s_cbranch_scc0 .LBB0_2490
	v_mov_b32_e32 v128, v165
	v_mov_b32_e32 v163, v129
	s_branch .LBB0_2492
